# attention work stealing: per-workgroup LDS 'queue exhausted' flags + wave-rotated remote-queue order, so most failing dequeue atomics are skipped
# speedup vs baseline: 1.0469x; 1.0031x over previous
; __device__ __forceinline__ AtdAddr atd_addr(const bf16* Kbase  , const bf16* Vbase  , int lane) {
;     AtdAddr a; const int ql = lane & 31, hi = lane >> 5;
;     a.KgE = Kbase + (size_t)(lane >> 3) * 3072 + (((lane & 7) ^ (lane >> 4)) * 8);
;     a.KgO = Kbase + (size_t)(lane >> 3) * 3072 + (((lane & 7) ^ (4 + (lane >> 4))) * 8);
;     { const int bsel = ((lane >> 4) & 1) << 2, a0 = lane >> 5;
;       a.VgE = Vbase + (size_t)(lane >> 3) * 3072 + (((lane & 7) ^ (bsel | a0)) * 8);
;       a.VgO = Vbase + (size_t)(lane >> 3) * 3072 + (((lane & 7) ^ (bsel | (2 + a0))) * 8); }
; #pragma unroll
;     for (int d0 = 0; d0 < 4; ++d0) a.koff[d0] = ql * 128 + (((2 * d0 + hi) ^ ((ql >> 1) & 7)) << 4);
;     { const int q = (lane & 15) >> 2, p = lane & 3, h1 = (lane >> 4) & 1;
; #pragma unroll
;       for (int pt = 0; pt < 2; ++pt)
; #pragma unroll
;         for (int dh = 0; dh < 2; ++dh) { const int row = 8 * pt + 4 * hi + q, sw = (((row >> 1) & 1) << 2) | ((row >> 2) & 3), ch = 4 * dh + 2 * h1 + (p >> 1);
;             a.voff[pt][dh] = ATD_V + row * 128 + ((ch ^ sw) << 4) + (p & 1) * 8; } }
;     return a;
; }
; __device__ __forceinline__ void phase_attn(const Ctx& C, const float* relb  , int layer) {
;     ...
;       for (int k = 0; k < 8; ++k) { const int x = (((int)blockIdx.x & 7) + k * (1 + 2 * (((int)blockIdx.x >> 3) & 3))) & 7;
;           unsigned* qb_ = (unsigned*)(ws_ + WS_BAR) + WQ_WORD + 64 * (8 * layer + x);
;           unsigned* qa_ = (unsigned*)(ws_ + WS_BAR) + WQ_WORD + 64 * (16 + 8 * layer + x);
;           for (;;) {
;               unsigned idx = 0;
;               if (lane == 0) idx = __hip_atomic_fetch_add(qb_, 1u, __ATOMIC_RELAXED, __HIP_MEMORY_SCOPE_AGENT);
;               idx = (unsigned)__builtin_amdgcn_readfirstlane((int)idx);
;               if (idx >= (unsigned)per_q) break;
.LBB0_260:
	v_writelane_b32 v255, s1, 42
	s_or_b64 exec, exec, s[4:5]
	s_mov_b64 s[100:101], exec
	s_mov_b64 exec, 0xffff
	v_lshlrev_b32_e32 v226, 2, v162
	v_add_u32_e32 v226, 0x23800, v226
	v_mov_b32_e32 v227, 0
	ds_write_b32 v226, v227
	s_mov_b64 exec, s[100:101]
	s_waitcnt lgkmcnt(0)
	s_add_u32 s14, s12, 0x7400000
	s_addc_u32 s15, s13, 0
	s_add_u32 s4, s12, 0x13400000
	v_ashrrev_i32_e32 v2, 4, v4
	s_addc_u32 s5, s13, 0
	s_lshl_b32 s10, s68, 16
	v_bitop3_b32 v3, v4, v2, 7 bitop3:0x6c
	s_lshl_b64 s[2:3], s[10:11], 2
	v_lshlrev_b32_e32 v118, 3, v3
	v_add_u32_e32 v3, 4, v2
	s_add_u32 s20, s12, s2
	v_ashrrev_i32_e32 v1, 3, v4
	s_movk_i32 s2, 0xc00
	v_bitop3_b32 v3, v3, v4, 7 bitop3:0x78
	v_and_b32_e32 v2, 1, v2
	s_addc_u32 s21, s13, s3
	v_ashrrev_i32_e32 v0, 5, v4
	v_mad_i64_i32 v[116:117], s[2:3], v1, s2, 0
	v_and_b32_e32 v1, 7, v4
	v_lshlrev_b32_e32 v120, 3, v3
	v_lshlrev_b32_e32 v3, 2, v2
	v_bitop3_b32 v5, v3, v1, v0 bitop3:0x36
	v_lshlrev_b32_e32 v122, 3, v5
	v_add_u32_e32 v5, 2, v0
	v_bitop3_b32 v1, v3, v1, v5 bitop3:0x36
	v_lshlrev_b32_e32 v124, 3, v1
	v_lshlrev_b32_e32 v1, 7, v4
	v_lshrrev_b32_e32 v3, 1, v4
	v_and_b32_e32 v1, 0xf80, v1
	v_bitop3_b32 v5, v5, v3, 7 bitop3:0x78
	v_lshl_add_u32 v137, v5, 4, v1
	v_add_u32_e32 v5, 4, v0
	v_bitop3_b32 v5, v5, v3, 7 bitop3:0x78
	v_lshl_add_u32 v150, v5, 4, v1
	v_add_u32_e32 v5, 6, v0
	v_bitop3_b32 v6, v3, v0, 7 bitop3:0x6c
	v_bitop3_b32 v5, v5, v3, 7 bitop3:0x78
	v_lshl_add_u32 v115, v6, 4, v1
	v_lshl_add_u32 v151, v5, 4, v1
	v_bfe_u32 v1, v4, 2, 2
	v_lshlrev_b32_e32 v126, 2, v0
	v_and_b32_e32 v3, 4, v3
	v_lshlrev_b32_e32 v2, 1, v2
	v_bfe_u32 v5, v4, 1, 1
	v_lshlrev_b32_e32 v7, 3, v4
	v_or_b32_e32 v6, v2, v5
	v_and_b32_e32 v7, 8, v7
	v_or_b32_e32 v8, v126, v1
	v_and_or_b32 v9, v0, 3, v3
	v_bitop3_b32 v2, v2, v9, v5 bitop3:0x36
	v_bitop3_b32 v9, v6, v9, 4 bitop3:0x36
	v_lshlrev_b32_e32 v128, 3, v0
	v_lshl_or_b32 v0, v8, 7, v7
	v_and_b32_e32 v114, 31, v4
	v_lshl_or_b32 v152, v2, 4, v0
	v_lshl_or_b32 v154, v9, 4, v0
	v_or_b32_e32 v0, 1, v126
	v_cmp_lt_i32_e64 s[42:43], v0, v114
	v_or_b32_e32 v0, 2, v126
	v_cmp_lt_i32_e64 s[44:45], v0, v114
	v_or_b32_e32 v0, 3, v126
	v_cmp_lt_i32_e64 s[46:47], v0, v114
	v_add_u32_e32 v0, 9, v126
	v_cmp_lt_i32_e64 s[50:51], v0, v114
	v_add_u32_e32 v0, 10, v126
	v_cmp_lt_i32_e64 s[52:53], v0, v114
	v_add_u32_e32 v0, 11, v126
	v_cmp_lt_i32_e64 s[54:55], v0, v114
	v_add_u32_e32 v0, 16, v126
	v_cmp_lt_i32_e64 s[56:57], v0, v114
	v_add_u32_e32 v0, 17, v126
	v_cmp_lt_i32_e64 s[58:59], v0, v114
	v_add_u32_e32 v0, 18, v126
	s_add_u32 s1, s12, 0x3800
	v_cmp_lt_i32_e64 s[60:61], v0, v114
	v_add_u32_e32 v0, 19, v126
	v_writelane_b32 v255, s1, 43
	s_addc_u32 s1, s13, 0
	v_cmp_lt_i32_e64 s[62:63], v0, v114
	v_add_u32_e32 v0, 24, v126
	v_writelane_b32 v255, s1, 44
	v_add_u32_e32 v10, 8, v126
	v_cmp_lt_i32_e64 s[64:65], v0, v114
	v_add_u32_e32 v0, 25, v126
	v_writelane_b32 v255, s68, 45
	v_or_b32_e32 v5, 4, v6
	v_or_b32_e32 v1, v10, v1
	v_bfe_u32 v11, v10, 2, 2
	v_cmp_lt_i32_e64 s[66:67], v0, v114
	v_add_u32_e32 v0, 26, v126
	v_writelane_b32 v255, s69, 46
	s_lshl_b32 s1, s68, 9
	v_bitop3_b32 v6, v11, v6, v3 bitop3:0x36
	v_bitop3_b32 v3, v11, v5, v3 bitop3:0x36
	v_lshl_or_b32 v1, v1, 7, v7
	v_cmp_lt_i32_e64 s[68:69], v0, v114
	v_add_u32_e32 v0, 27, v126
	v_lshlrev_b32_e32 v80, 2, v114
	v_lshl_or_b32 v153, v6, 4, v1
	v_lshl_or_b32 v155, v3, 4, v1
	v_cmp_lt_i32_e64 s[70:71], v0, v114
	v_lshl_add_u64 v[0:1], s[20:21], 0, v[80:81]
	s_mov_b64 s[2:3], 0x1d020000
	v_lshl_add_u64 v[130:131], v[0:1], 0, s[2:3]
	s_mov_b64 s[2:3], 0x1d000000
	v_writelane_b32 v255, s1, 47
	s_mov_b32 s19, 0
	v_cmp_eq_u32_e64 s[36:37], 0, v4
	v_ashrrev_i32_e32 v119, 31, v118
	v_ashrrev_i32_e32 v121, 31, v120
	v_ashrrev_i32_e32 v123, 31, v122
	v_ashrrev_i32_e32 v125, 31, v124
	v_ashrrev_i32_e32 v129, 31, v128
	v_cmp_gt_u32_e64 s[38:39], 32, v4
	v_cmp_lt_i32_e64 s[40:41], v126, v114
	v_cmp_lt_i32_e64 s[48:49], v10, v114
	v_ashrrev_i32_e32 v127, 31, v126
	v_lshl_add_u64 v[132:133], v[0:1], 0, s[2:3]
	s_waitcnt lgkmcnt(0)
	s_barrier
	s_branch .LBB0_262
.LBB0_261:
	v_mov_b32_e32 v226, s101
	v_mov_b32_e32 v227, 1
	ds_write_b32 v226, v227 offset:32
	s_add_i32 s19, s19, 1
	s_cmp_lg_u32 s19, 8
	s_cbranch_scc0 .LBB0_330
.LBB0_262:
	s_mov_b32 s100, s19
	s_cmp_eq_u32 s19, 0
	s_cbranch_scc1 .Lq_k0
	v_readlane_b32 s100, v254, 20
	s_nop 0
	s_add_i32 s100, s100, s19
	s_add_i32 s100, s100, -1
	s_cmp_lt_u32 s100, 7
	s_cbranch_scc1 .Lq_nomod
	s_sub_u32 s100, s100, 7
.Lq_nomod:
	s_add_i32 s100, s100, 1
.Lq_k0:
	v_readlane_b32 s2, v255, 7
	s_mul_i32 s2, s100, s2
	v_readlane_b32 s3, v254, 0
	s_add_i32 s2, s2, s3
	s_mov_b32 s1, s78
	s_and_b32 s78, s2, 7
	s_lshl_b32 s2, s78, 6
	v_readlane_b32 s3, v255, 47
	s_or_b32 s10, s2, s3
	s_lshl_b64 s[2:3], s[10:11], 2
	v_readlane_b32 s10, v255, 43
	s_add_u32 s20, s10, s2
	v_readlane_b32 s2, v255, 44
	s_addc_u32 s21, s2, s3
	s_lshl_b32 s2, s78, 12
	s_mul_i32 s3, s78, 0x1800000
	s_add_u32 s12, s14, s3
	s_addc_u32 s13, s15, 0
	v_lshl_add_u64 v[134:135], v[116:117], 1, s[12:13]
	s_mov_b64 s[12:13], 0x1400
	s_lshl_b32 s10, s78, 14
	v_lshl_add_u64 v[98:99], v[134:135], 0, s[12:13]
	v_or_b32_e32 v136, s2, v114
	v_lshl_add_u64 v[100:101], v[130:131], 0, s[10:11]
	s_lshl_b32 s101, s78, 2
	s_add_i32 s101, s101, 0x23800
	v_mov_b32_e32 v226, s101
	ds_read_b32 v227, v226
	s_waitcnt lgkmcnt(0)
	v_readfirstlane_b32 s98, v227
	s_nop 0
	s_cmp_lg_u32 s98, 0
	s_cbranch_scc1 .LBB0_299
	s_branch .LBB0_265

; __device__ __forceinline__ void phase_attn(const Ctx& C, const float* relb  , int layer) {
;     ...
;               const int bh = x * 8 + (int)(idx >> 7), qi = 127 - (int)(idx & 127);
;               attnB_wave(st, QKV, O, sso, bh >> 3, bh & 7, qi, lane);
;           }
;           for (;;) {
;               unsigned idx = 0;
;               if (lane == 0) idx = __hip_atomic_fetch_add(qa_, 1u, __ATOMIC_RELAXED, __HIP_MEMORY_SCOPE_AGENT);
;               idx = (unsigned)__builtin_amdgcn_readfirstlane((int)idx);
;               if (idx >= (unsigned)per_q) break;
.LBB0_299:
	v_mov_b32_e32 v226, s101
	v_mov_b32_e32 v227, 1
	ds_write_b32 v226, v227
	ds_read_b32 v228, v226 offset:32
	s_add_u32 s20, s20, 0x1000
	s_addc_u32 s21, s21, 0
	s_lshl_b32 s10, s2, 2
	v_lshl_add_u64 v[138:139], v[134:135], 0, s[90:91]
	v_lshl_add_u64 v[140:141], v[132:133], 0, s[10:11]
	s_mov_b32 s78, s1
	s_waitcnt lgkmcnt(0)
	v_readfirstlane_b32 s99, v228
	s_nop 0
	s_cmp_lg_u32 s99, 0
	s_cbranch_scc1 .LBB0_261
	s_branch .LBB0_302
